# prepA: loop-invariant gain loads hoisted out of the row loop, k-part and rope-table loads issued at the top of the iteration, exact vmcnt counts (on keep_v7)
# baseline (speedup 1.0000x reference)
.LBB0_302:
	s_andn2_b64 vcc, exec, s[2:3]
	s_cbranch_vccnz .LBB0_617
	v_readlane_b32 s2, v255, 0
	v_mbcnt_lo_u32_b32 v14, -1, 0
	v_mbcnt_hi_u32_b32 v14, -1, v14
	v_readlane_b32 s3, v255, 1
	s_nop 0
	v_add_u32_e32 v0, s2, v14
	s_nop 0
	v_readfirstlane_b32 s2, v0
	s_ashr_i32 s2, s2, 6
	s_add_i32 s14, s2, s3
	s_mov_b64 s[2:3], s[0:1]
	s_cmp_gt_i32 s14, 0x8fff
	s_cbranch_scc1 .LBB0_313
	s_load_dwordx2 s[12:13], s[2:3], 0x58
	s_load_dwordx2 s[16:17], s[2:3], 0x68
	s_load_dwordx2 s[18:19], s[2:3], 0x128
	s_load_dwordx4 s[4:7], s[2:3], 0x88
	v_lshlrev_b32_e32 v0, 4, v14
	s_waitcnt vmcnt(1)
	v_and_b32_e32 v12, 63, v14
	v_and_b32_e32 v0, 0x70, v0
	v_lshlrev_b32_e32 v16, 4, v12
	v_mov_b32_e32 v17, v1
	s_waitcnt lgkmcnt(0)
	v_lshl_add_u64 v[6:7], s[4:5], 0, v[0:1]
	s_mul_i32 s5, s14, 0xb00
	v_lshl_add_u64 v[2:3], s[12:13], 0, v[16:17]
	s_mul_hi_i32 s4, s14, 0xb00
	s_add_u32 s12, s18, s5
	v_lshlrev_b32_e32 v14, 3, v14
	v_lshl_add_u64 v[10:11], s[18:19], 0, v[0:1]
	s_mov_b64 s[2:3], 0x200000
	s_addc_u32 s13, s19, s4
	v_and_b32_e32 v17, 56, v14
	s_movk_i32 s4, 0x80
	v_lshlrev_b32_e32 v15, 2, v12
	v_lshlrev_b32_e32 v18, 3, v12
	v_mov_b32_e32 v19, v1
	v_lshl_add_u64 v[8:9], v[10:11], 0, s[2:3]
	s_mov_b64 s[2:3], 0x240000
	v_and_or_b32 v14, v16, s4, v17
	s_movk_i32 s4, 0x380
	v_xor_b32_e32 v38, 4, v15
	v_xor_b32_e32 v39, 8, v15
	v_xor_b32_e32 v40, 16, v15
	v_xor_b32_e32 v41, 32, v15
	v_xor_b32_e32 v42, 64, v15
	v_xor_b32_e32 v43, 0x80, v15
	v_lshl_add_u64 v[4:5], s[16:17], 0, v[18:19]
	v_lshl_add_u64 v[10:11], v[10:11], 0, s[2:3]
	v_cmp_gt_u32_e64 s[2:3], 16, v12
	v_lshl_add_u64 v[12:13], s[6:7], 0, v[0:1]
	v_or_b32_e32 v0, 0xac00200, v15
	v_mov_b32_e32 v15, v1
	v_and_or_b32 v16, v16, s4, v17
	v_mov_b32_e32 v17, v1
	v_or_b32_e32 v18, 0xac00000, v18
	global_load_dwordx4 v[100:103], v[2:3], off
	global_load_dwordx2 v[104:105], v[4:5], off
	global_load_dwordx4 v[106:109], v[6:7], off
	global_load_dwordx4 v[110:113], v[6:7], off offset:128
	global_load_dwordx4 v[114:117], v[12:13], off
	global_load_dwordx4 v[118:121], v[12:13], off offset:128
	s_waitcnt vmcnt(0)
	s_branch .LBB0_306

.LBB0_306:
	s_and_b32 s100, s14, 0x7ff
	s_lshl_b32 s100, s100, 7
	s_mov_b32 s101, 0
	v_lshl_add_u64 v[26:27], s[12:13], 0, v[18:19]
	global_load_dwordx2 v[20:21], v[26:27], off
	v_lshl_add_u64 v[22:23], s[12:13], 0, v[16:17]
	v_add_co_u32_e32 v28, vcc, 0xac00000, v22
	v_lshl_add_u64 v[24:25], s[12:13], 0, v[0:1]
	s_nop 0
	v_addc_co_u32_e32 v29, vcc, 0, v23, vcc
	global_load_dword v49, v[24:25], off
	global_load_dwordx2 v[30:31], v[28:29], off offset:832
	s_nop 0
	global_load_dwordx2 v[28:29], v[28:29], off offset:896
	s_mov_b32 s98, 0xac00000
	s_mov_b32 s99, 0
	v_lshl_add_u64 v[134:135], s[12:13], 0, v[14:15]
	v_lshl_add_u64 v[134:135], v[134:135], 0, s[98:99]
	v_lshl_add_u64 v[136:137], v[8:9], 0, s[100:101]
	v_lshl_add_u64 v[138:139], v[10:11], 0, s[100:101]
	global_load_dwordx2 v[122:123], v[134:135], off offset:1856
	global_load_dwordx2 v[124:125], v[134:135], off offset:1920
	global_load_dwordx4 v[126:129], v[136:137], off
	global_load_dwordx4 v[130:133], v[138:139], off
	s_cmp_lt_i32 s14, 0x8000
	s_waitcnt vmcnt(7)
	v_and_b32_e32 v37, 0xffff0000, v21
	v_and_b32_e32 v45, 0xffff0000, v20
	v_lshlrev_b32_e32 v36, 16, v21
	v_lshlrev_b32_e32 v44, 16, v20
	v_mov_b32_e32 v46, v45
	v_mov_b32_e32 v47, v37
	v_mov_b32_e32 v20, v44
	v_mov_b32_e32 v21, v36
	v_pk_mul_f32 v[46:47], v[46:47], v[46:47]
	s_nop 0
	v_pk_fma_f32 v[20:21], v[20:21], v[20:21], v[46:47]
	s_nop 0
	v_add_f32_e32 v20, v20, v21
	ds_bpermute_b32 v21, v38, v20
	s_waitcnt lgkmcnt(0)
	v_add_f32_e32 v20, v20, v21
	ds_bpermute_b32 v21, v39, v20
	s_waitcnt lgkmcnt(0)
	v_add_f32_e32 v20, v20, v21
	ds_bpermute_b32 v21, v40, v20
	s_waitcnt lgkmcnt(0)
	v_add_f32_e32 v20, v20, v21
	ds_bpermute_b32 v21, v41, v20
	s_waitcnt lgkmcnt(0)
	v_add_f32_e32 v20, v20, v21
	ds_bpermute_b32 v21, v42, v20
	s_waitcnt lgkmcnt(0)
	v_add_f32_e32 v20, v20, v21
	ds_bpermute_b32 v21, v43, v20
	s_waitcnt lgkmcnt(0)
	v_add_f32_e32 v20, v20, v21
	v_fmamk_f32 v20, v20, 0x3b800000, v240
	v_mul_f32_e32 v21, 0x4f800000, v20
	v_cmp_gt_f32_e32 vcc, s77, v20
	s_nop 1
	v_cndmask_b32_e32 v46, v20, v21, vcc
	v_sqrt_f32_e32 v47, v46
	v_lshl_add_u64 v[20:21], s[12:13], 0, v[14:15]
	v_add_u32_e32 v48, -1, v47
	v_add_u32_e32 v50, 1, v47
	v_fma_f32 v51, -v48, v47, v46
	v_fma_f32 v52, -v50, v47, v46
	v_cmp_ge_f32_e64 s[4:5], 0, v51
	s_nop 1
	v_cndmask_b32_e64 v47, v47, v48, s[4:5]
	v_cmp_lt_f32_e64 s[4:5], 0, v52
	s_nop 1
	v_cndmask_b32_e64 v47, v47, v50, s[4:5]
	v_mul_f32_e32 v48, 0x37800000, v47
	v_cndmask_b32_e32 v47, v47, v48, vcc
	v_cmp_class_f32_e32 vcc, v46, v241
	s_nop 1
	v_cndmask_b32_e32 v46, v47, v46, vcc
	v_div_scale_f32 v47, s[4:5], v46, v46, 1.0
	v_rcp_f32_e32 v50, v47
	v_div_scale_f32 v51, s[6:7], 1.0, v46, 1.0
	v_add_co_u32_e32 v48, vcc, 0xac00000, v20
	v_fma_f32 v52, -v47, v50, 1.0
	v_fmac_f32_e32 v50, v52, v50
	v_mul_f32_e32 v52, v51, v50
	v_fma_f32 v53, -v47, v52, v51
	v_fmac_f32_e32 v52, v53, v50
	v_fma_f32 v47, -v47, v52, v51
	s_mov_b64 s[4:5], vcc
	s_mov_b64 vcc, s[6:7]
	v_div_fmas_f32 v47, v47, v50, v52
	v_div_fixup_f32 v46, v47, v46, 1.0
	v_pk_mul_f32 v[44:45], v[46:47], v[44:45] op_sel_hi:[0,1]
	v_pk_mul_f32 v[36:37], v[46:47], v[36:37] op_sel_hi:[0,1]
	v_mov_b64_e32 v[32:33], v[100:101]
	v_mov_b64_e32 v[34:35], v[102:103]
	v_pk_mul_f32 v[32:33], v[32:33], v[44:45]
	v_pk_mul_f32 v[34:35], v[34:35], v[36:37]
	v_cvt_pk_bf16_f32 v32, v32, v33
	v_cvt_pk_bf16_f32 v33, v34, v35
	global_store_dwordx2 v[26:27], v[32:33], off
	s_waitcnt vmcnt(5)
	v_lshlrev_b32_e32 v32, 16, v49
	v_and_b32_e32 v33, 0xffff0000, v49
	v_pk_mul_f32 v[34:35], v[32:33], v[32:33]
	v_and_b32_e32 v50, 0xffff0000, v29
	v_add_f32_e32 v34, v34, v35
	ds_bpermute_b32 v35, v38, v34
	v_lshlrev_b32_e32 v51, 16, v29
	s_waitcnt lgkmcnt(0)
	v_add_f32_e32 v34, v34, v35
	ds_bpermute_b32 v35, v39, v34
	s_waitcnt lgkmcnt(0)
	v_add_f32_e32 v34, v34, v35
	ds_bpermute_b32 v35, v40, v34
	s_waitcnt lgkmcnt(0)
	v_add_f32_e32 v34, v34, v35
	ds_bpermute_b32 v35, v41, v34
	s_waitcnt lgkmcnt(0)
	v_add_f32_e32 v34, v34, v35
	ds_bpermute_b32 v35, v42, v34
	s_waitcnt lgkmcnt(0)
	v_add_f32_e32 v34, v34, v35
	ds_bpermute_b32 v35, v43, v34
	s_waitcnt lgkmcnt(0)
	v_add_f32_e32 v34, v34, v35
	v_fmamk_f32 v34, v34, 0x3c000000, v240
	v_mul_f32_e32 v35, 0x4f800000, v34
	v_cmp_gt_f32_e32 vcc, s77, v34
	s_nop 1
	v_cndmask_b32_e32 v34, v34, v35, vcc
	v_sqrt_f32_e32 v35, v34
	s_nop 0
	v_add_u32_e32 v36, -1, v35
	v_add_u32_e32 v37, 1, v35
	v_fma_f32 v44, -v36, v35, v34
	v_fma_f32 v45, -v37, v35, v34
	v_cmp_ge_f32_e64 s[6:7], 0, v44
	s_nop 1
	v_cndmask_b32_e64 v35, v35, v36, s[6:7]
	v_cmp_lt_f32_e64 s[6:7], 0, v45
	s_nop 1
	v_cndmask_b32_e64 v35, v35, v37, s[6:7]
	v_mul_f32_e32 v36, 0x37800000, v35
	v_cndmask_b32_e32 v35, v35, v36, vcc
	v_cmp_class_f32_e32 vcc, v34, v241
	s_nop 1
	v_cndmask_b32_e32 v34, v35, v34, vcc
	v_div_scale_f32 v35, s[6:7], v34, v34, 1.0
	v_rcp_f32_e32 v36, v35
	v_div_scale_f32 v37, vcc, 1.0, v34, 1.0
	s_cselect_b64 s[6:7], -1, 0
	v_fma_f32 v44, -v35, v36, 1.0
	v_fmac_f32_e32 v36, v44, v36
	v_mul_f32_e32 v44, v37, v36
	v_fma_f32 v45, -v35, v44, v37
	v_fmac_f32_e32 v44, v45, v36
	v_fma_f32 v35, -v35, v44, v37
	v_div_fmas_f32 v35, v35, v36, v44
	v_div_fixup_f32 v34, v35, v34, 1.0
	v_pk_mul_f32 v[32:33], v[34:35], v[32:33] op_sel_hi:[0,1]
	v_mov_b64_e32 v[26:27], v[104:105]
	v_pk_mul_f32 v[26:27], v[26:27], v[32:33]
	v_addc_co_u32_e64 v49, vcc, 0, v21, s[4:5]
	v_cvt_pk_bf16_f32 v26, v26, v27
	global_store_dword v[24:25], v26, off
	v_mov_b64_e32 v[34:35], v[106:107]
	v_mov_b64_e32 v[36:37], v[108:109]
	v_mov_b64_e32 v[44:45], v[110:111]
	v_mov_b64_e32 v[46:47], v[112:113]
	s_nop 0
	s_waitcnt vmcnt(4)
	v_mov_b64_e32 v[26:27], v[122:123]
	v_mov_b64_e32 v[24:25], v[124:125]
	v_and_b32_e32 v48, 0xffff0000, v31
	v_lshlrev_b32_e32 v49, 16, v31
	v_lshlrev_b32_e32 v32, 16, v30
	v_and_b32_e32 v33, 0xffff0000, v30
	v_lshlrev_b32_e32 v30, 16, v28
	v_and_b32_e32 v31, 0xffff0000, v28
	v_pk_mul_f32 v[52:53], v[30:31], v[30:31]
	v_pk_mul_f32 v[28:29], v[50:51], v[50:51]
	v_pk_fma_f32 v[52:53], v[32:33], v[32:33], v[52:53]
	v_pk_fma_f32 v[28:29], v[48:49], v[48:49], v[28:29]
	v_add_f32_e32 v52, v52, v53
	v_add_f32_e32 v29, v29, v52
	v_add_f32_e32 v28, v28, v29
	ds_bpermute_b32 v29, v38, v28
	s_and_b32 s9, s14, 0x7ff
	s_cmpk_gt_i32 s14, 0x7fff
	s_waitcnt lgkmcnt(0)
	v_add_f32_e32 v28, v28, v29
	ds_bpermute_b32 v29, v39, v28
	s_waitcnt lgkmcnt(0)
	v_add_f32_e32 v28, v28, v29
	ds_bpermute_b32 v29, v40, v28
	s_waitcnt lgkmcnt(0)
	v_add_f32_e32 v28, v28, v29
	v_fmamk_f32 v28, v28, 0x3c800000, v240
	v_mul_f32_e32 v29, 0x4f800000, v28
	v_cmp_gt_f32_e32 vcc, s77, v28
	s_nop 1
	v_cndmask_b32_e32 v28, v28, v29, vcc
	v_sqrt_f32_e32 v29, v28
	s_nop 0
	v_add_u32_e32 v52, -1, v29
	v_add_u32_e32 v53, 1, v29
	v_fma_f32 v54, -v52, v29, v28
	v_fma_f32 v55, -v53, v29, v28
	v_cmp_ge_f32_e64 s[4:5], 0, v54
	s_nop 1
	v_cndmask_b32_e64 v29, v29, v52, s[4:5]
	v_cmp_lt_f32_e64 s[4:5], 0, v55
	s_nop 1
	v_cndmask_b32_e64 v29, v29, v53, s[4:5]
	v_mul_f32_e32 v52, 0x37800000, v29
	v_cndmask_b32_e32 v29, v29, v52, vcc
	v_cmp_class_f32_e32 vcc, v28, v241
	s_nop 1
	v_cndmask_b32_e32 v28, v29, v28, vcc
	v_div_scale_f32 v29, s[4:5], v28, v28, 1.0
	v_rcp_f32_e32 v52, v29
	v_div_scale_f32 v53, vcc, 1.0, v28, 1.0
	v_fma_f32 v54, -v29, v52, 1.0
	v_fmac_f32_e32 v52, v54, v52
	v_mul_f32_e32 v54, v53, v52
	v_fma_f32 v55, -v29, v54, v53
	v_fmac_f32_e32 v54, v55, v52
	v_fma_f32 v29, -v29, v54, v53
	v_div_fmas_f32 v29, v29, v52, v54
	v_div_fixup_f32 v52, v29, v28, 1.0
	v_pk_mul_f32 v[28:29], v[34:35], v[52:53] op_sel_hi:[1,0]
	v_pk_mul_f32 v[34:35], v[44:45], v[52:53] op_sel_hi:[1,0]
	v_mul_f32_e32 v44, v36, v52
	v_mul_f32_e32 v45, v46, v52
	v_mov_b32_e32 v36, v47
	v_pk_mul_f32 v[30:31], v[34:35], v[30:31]
	v_mul_f32_e32 v34, v45, v51
	v_pk_mul_f32 v[36:37], v[36:37], v[52:53] op_sel_hi:[1,0]
	v_mov_b32_e32 v51, v48
	v_pk_mul_f32 v[28:29], v[28:29], v[32:33]
	v_mul_f32_e32 v32, v44, v49
	v_pk_mul_f32 v[36:37], v[36:37], v[50:51]
	s_cbranch_scc1 .LBB0_308
	s_lshl_b32 s20, s9, 7
	v_lshl_add_u64 v[44:45], v[8:9], 0, s[20:21]
	v_lshl_add_u64 v[48:49], v[10:11], 0, s[20:21]
	s_waitcnt vmcnt(2)
	v_mov_b64_e32 v[44:45], v[126:127]
	v_mov_b64_e32 v[46:47], v[128:129]
	s_nop 0
	v_mov_b64_e32 v[48:49], v[130:131]
	v_mov_b64_e32 v[50:51], v[132:133]
	v_mul_f32_e32 v54, v32, v46
	v_mul_f32_e32 v56, v34, v50
	v_mul_f32_e32 v34, v34, v46
	v_mov_b32_e32 v46, v51
	v_mul_f32_e32 v58, v32, v50
	v_pk_mul_f32 v[32:33], v[36:37], v[46:47]
	v_mov_b32_e32 v50, v47
	v_mov_b32_e32 v55, v33
	v_mov_b32_e32 v57, v32
	v_pk_mul_f32 v[32:33], v[36:37], v[50:51]
	v_pk_mul_f32 v[52:53], v[30:31], v[48:49]
	v_pk_mul_f32 v[48:49], v[28:29], v[48:49]
	v_mov_b32_e32 v35, v32
	v_mov_b32_e32 v59, v33
	v_pk_fma_f32 v[28:29], v[28:29], v[44:45], v[52:53] neg_lo:[0,0,1] neg_hi:[0,0,1]
	v_pk_add_f32 v[32:33], v[54:55], v[56:57] neg_lo:[0,1] neg_hi:[0,1]
	v_pk_fma_f32 v[30:31], v[30:31], v[44:45], v[48:49]
	v_pk_add_f32 v[34:35], v[34:35], v[58:59]
	s_branch .LBB0_309

.LBB0_309:
	s_mov_b64 s[4:5], 0xac00340
	v_pk_mul_f32 v[28:29], v[28:29], s[76:77] op_sel_hi:[1,0]
	v_pk_mul_f32 v[32:33], v[32:33], s[76:77] op_sel_hi:[1,0]
	v_lshl_add_u64 v[36:37], v[22:23], 0, s[4:5]
	s_mov_b64 s[4:5], 0xac00380
	v_pk_mul_f32 v[30:31], v[30:31], s[76:77] op_sel_hi:[1,0]
	v_pk_mul_f32 v[34:35], v[34:35], s[76:77] op_sel_hi:[1,0]
	v_cvt_pk_bf16_f32 v28, v28, v29
	v_cvt_pk_bf16_f32 v29, v32, v33
	v_lshl_add_u64 v[22:23], v[22:23], 0, s[4:5]
	v_cvt_pk_bf16_f32 v30, v30, v31
	v_cvt_pk_bf16_f32 v31, v34, v35
	global_store_dwordx2 v[36:37], v[28:29], off
	global_store_dwordx2 v[22:23], v[30:31], off
	v_mov_b64_e32 v[30:31], v[114:115]
	v_mov_b64_e32 v[32:33], v[116:117]
	s_nop 0
	v_mov_b64_e32 v[34:35], v[118:119]
	v_mov_b64_e32 v[36:37], v[120:121]
	v_and_b32_e32 v28, 0xffff0000, v27
	v_lshlrev_b32_e32 v29, 16, v27
	v_lshlrev_b32_e32 v22, 16, v26
	v_and_b32_e32 v23, 0xffff0000, v26
	v_lshlrev_b32_e32 v26, 16, v24
	v_and_b32_e32 v27, 0xffff0000, v24
	v_and_b32_e32 v44, 0xffff0000, v25
	v_lshlrev_b32_e32 v45, 16, v25
	v_pk_mul_f32 v[46:47], v[26:27], v[26:27]
	v_pk_mul_f32 v[24:25], v[44:45], v[44:45]
	v_pk_fma_f32 v[46:47], v[22:23], v[22:23], v[46:47]
	v_pk_fma_f32 v[24:25], v[28:29], v[28:29], v[24:25]
	v_add_f32_e32 v46, v46, v47
	v_add_f32_e32 v25, v25, v46
	v_add_f32_e32 v24, v24, v25
	ds_bpermute_b32 v25, v38, v24
	s_waitcnt lgkmcnt(0)
	v_add_f32_e32 v24, v24, v25
	ds_bpermute_b32 v25, v39, v24
	s_waitcnt lgkmcnt(0)
	v_add_f32_e32 v24, v24, v25
	ds_bpermute_b32 v25, v40, v24
	s_waitcnt lgkmcnt(0)
	v_add_f32_e32 v24, v24, v25
	v_fmamk_f32 v24, v24, 0x3c800000, v240
	v_mul_f32_e32 v25, 0x4f800000, v24
	v_cmp_gt_f32_e32 vcc, s77, v24
	s_nop 1
	v_cndmask_b32_e32 v24, v24, v25, vcc
	v_sqrt_f32_e32 v25, v24
	s_nop 0
	v_add_u32_e32 v46, -1, v25
	v_add_u32_e32 v47, 1, v25
	v_fma_f32 v48, -v46, v25, v24
	v_fma_f32 v49, -v47, v25, v24
	v_cmp_ge_f32_e64 s[4:5], 0, v48
	s_nop 1
	v_cndmask_b32_e64 v25, v25, v46, s[4:5]
	v_cmp_lt_f32_e64 s[4:5], 0, v49
	s_nop 1
	v_cndmask_b32_e64 v25, v25, v47, s[4:5]
	v_mul_f32_e32 v46, 0x37800000, v25
	v_cndmask_b32_e32 v25, v25, v46, vcc
	v_cmp_class_f32_e32 vcc, v24, v241
	s_nop 1
	v_cndmask_b32_e32 v24, v25, v24, vcc
	v_div_scale_f32 v25, s[4:5], v24, v24, 1.0
	v_rcp_f32_e32 v46, v25
	v_div_scale_f32 v47, vcc, 1.0, v24, 1.0
	v_fma_f32 v48, -v25, v46, 1.0
	v_fmac_f32_e32 v46, v48, v46
	v_mul_f32_e32 v48, v47, v46
	v_fma_f32 v49, -v25, v48, v47
	v_fmac_f32_e32 v48, v49, v46
	v_fma_f32 v25, -v25, v48, v47
	v_div_fmas_f32 v25, v25, v46, v48
	v_div_fixup_f32 v46, v25, v24, 1.0
	s_andn2_b64 vcc, exec, s[6:7]
	v_pk_mul_f32 v[24:25], v[30:31], v[46:47] op_sel_hi:[1,0]
	v_pk_mul_f32 v[30:31], v[34:35], v[46:47] op_sel_hi:[1,0]
	v_mul_f32_e32 v34, v32, v46
	v_mul_f32_e32 v35, v36, v46
	v_mov_b32_e32 v32, v37
	v_pk_mul_f32 v[24:25], v[24:25], v[22:23]
	v_pk_mul_f32 v[22:23], v[30:31], v[26:27]
	v_mul_f32_e32 v30, v35, v45
	v_pk_mul_f32 v[32:33], v[32:33], v[46:47] op_sel_hi:[1,0]
	v_mov_b32_e32 v45, v28
	v_mul_f32_e32 v26, v34, v29
	v_pk_mul_f32 v[28:29], v[32:33], v[44:45]
	s_cbranch_vccnz .LBB0_311
	s_lshl_b32 s20, s9, 7
	v_lshl_add_u64 v[32:33], v[8:9], 0, s[20:21]
	v_lshl_add_u64 v[36:37], v[10:11], 0, s[20:21]
	s_waitcnt vmcnt(4)
	v_mov_b64_e32 v[32:33], v[126:127]
	v_mov_b64_e32 v[34:35], v[128:129]
	s_nop 0
	v_mov_b64_e32 v[44:45], v[130:131]
	v_mov_b64_e32 v[46:47], v[132:133]
	v_mul_f32_e32 v48, v26, v34
	v_mul_f32_e32 v50, v30, v46
	v_mul_f32_e32 v30, v30, v34
	v_mov_b32_e32 v34, v47
	v_mul_f32_e32 v52, v26, v46
	v_pk_mul_f32 v[26:27], v[28:29], v[34:35]
	v_mov_b32_e32 v46, v35
	v_mov_b32_e32 v49, v27
	v_mov_b32_e32 v51, v26
	v_pk_mul_f32 v[26:27], v[28:29], v[46:47]
	v_pk_mul_f32 v[36:37], v[22:23], v[44:45]
	v_mov_b32_e32 v31, v26
	v_mov_b32_e32 v53, v27
	v_pk_mul_f32 v[44:45], v[24:25], v[44:45]
	v_pk_add_f32 v[26:27], v[48:49], v[50:51] neg_lo:[0,1] neg_hi:[0,1]
	v_pk_add_f32 v[30:31], v[30:31], v[52:53]
	v_pk_fma_f32 v[24:25], v[24:25], v[32:33], v[36:37] neg_lo:[0,0,1] neg_hi:[0,0,1]
	v_pk_fma_f32 v[22:23], v[22:23], v[32:33], v[44:45]
	v_mov_b32_e32 v28, v31
	v_mov_b32_e32 v29, v27
